# bias (sh2.W1) loop rewritten: 4 columns per wave processed together, 16 cross-lane reductions batched (was 16 serialized load+6-step bpermute chains); stacks on P4,P5,P8 epilogues
# speedup vs baseline: 1.0073x; 1.0073x over previous
; __device__ __forceinline__ float bflo(unsigned w) { return __uint_as_float(w << 16); }
; __device__ __forceinline__ float bfhi(unsigned w) { return __uint_as_float(w & 0xffff0000u); }
; __device__ __forceinline__ void bias_phase(const bf16_t* W1T, const float* mod, float* cb, int gw, int NGW, int lane) {
;     for (int n = gw; n < HID; n += NGW) {
;         float w[32];
; #pragma unroll
;         for (int j = 0; j < 4; ++j) { const u32x4 r = *(const u32x4*)(W1T + (size_t)n * DM + (j * 64 + lane) * 8);
;             w[8 * j + 0] = bflo(r.x); w[8 * j + 1] = bfhi(r.x); w[8 * j + 2] = bflo(r.y); w[8 * j + 3] = bfhi(r.y); w[8 * j + 4] = bflo(r.z); w[8 * j + 5] = bfhi(r.z); w[8 * j + 6] = bflo(r.w); w[8 * j + 7] = bfhi(r.w); }
; #pragma unroll
;         for (int b = 0; b < 4; ++b) { const float* sh = mod + (size_t)b * NMOD + 3 * DM; float s = 0.f;
; #pragma unroll
;             for (int j = 0; j < 4; ++j) { const f32x4 s0 = *(const f32x4*)(sh + (j * 64 + lane) * 8), s1 = *(const f32x4*)(sh + (j * 64 + lane) * 8 + 4);
;                 s += (w[8 * j + 0] * s0.x + w[8 * j + 1] * s0.y) + (w[8 * j + 2] * s0.z + w[8 * j + 3] * s0.w) + (w[8 * j + 4] * s1.x + w[8 * j + 5] * s1.y) + (w[8 * j + 6] * s1.z + w[8 * j + 7] * s1.w); }
;             s = wave_sum(s);
;             if (lane == 0) cb[(size_t)b * HID + n] = s; }
;     }
.LBB0_411:
	s_waitcnt lgkmcnt(0)
	s_add_u32 s98, s48, 0x3700000
	s_addc_u32 s99, s49, 0
	v_lshlrev_b32_e32 v0, 5, v160
	v_add_u32_e32 v1, 0x1000, v0
	v_mov_b32_e32 v2, 0
	v_mov_b32_e32 v3, 0
	v_mov_b32_e32 v4, 0
	v_mov_b32_e32 v5, 0
	v_mov_b32_e32 v6, 0
	v_mov_b32_e32 v7, 0
	v_mov_b32_e32 v8, 0
	v_mov_b32_e32 v9, 0
	v_mov_b32_e32 v10, 0
	v_mov_b32_e32 v11, 0
	v_mov_b32_e32 v12, 0
	v_mov_b32_e32 v13, 0
	v_mov_b32_e32 v14, 0
	v_mov_b32_e32 v15, 0
	v_mov_b32_e32 v16, 0
	v_mov_b32_e32 v17, 0
	s_add_u32 s8, s48, s0
	s_addc_u32 s9, s49, s1
	v_mov_b32_e32 v26, v32
	s_mul_i32 s10, s6, 1
	v_add_u32_e32 v27, s10, v32
	global_load_dwordx4 v[44:47], v26, s[98:99]
	global_load_dwordx4 v[48:51], v26, s[98:99] offset:1024
	global_load_dwordx4 v[52:55], v26, s[98:99] offset:2048
	global_load_dwordx4 v[56:59], v26, s[98:99] offset:3072
	global_load_dwordx4 v[60:63], v27, s[98:99]
	global_load_dwordx4 v[64:67], v27, s[98:99] offset:1024
	global_load_dwordx4 v[68:71], v27, s[98:99] offset:2048
	global_load_dwordx4 v[72:75], v27, s[98:99] offset:3072
	s_add_u32 s100, s48, 0x6000
	s_addc_u32 s101, s49, 0
	global_load_dwordx4 v[76:79], v0, s[100:101]
	global_load_dwordx4 v[80:83], v0, s[100:101] offset:16
	global_load_dwordx4 v[84:87], v0, s[100:101] offset:2048
	global_load_dwordx4 v[98:101], v0, s[100:101] offset:2064
	global_load_dwordx4 v[102:105], v1, s[100:101]
	global_load_dwordx4 v[106:109], v1, s[100:101] offset:16
	global_load_dwordx4 v[110:113], v1, s[100:101] offset:2048
	global_load_dwordx4 v[114:117], v1, s[100:101] offset:2064
	s_waitcnt vmcnt(0)
	v_lshlrev_b32_e32 v18, 16, v44
	v_and_b32_e32 v19, 0xffff0000, v44
	v_fmac_f32_e32 v2, v76, v18
	v_fmac_f32_e32 v2, v77, v19
	v_lshlrev_b32_e32 v20, 16, v60
	v_and_b32_e32 v21, 0xffff0000, v60
	v_fmac_f32_e32 v6, v76, v20
	v_fmac_f32_e32 v6, v77, v21
	v_lshlrev_b32_e32 v22, 16, v45
	v_and_b32_e32 v23, 0xffff0000, v45
	v_fmac_f32_e32 v2, v78, v22
	v_fmac_f32_e32 v2, v79, v23
	v_lshlrev_b32_e32 v24, 16, v61
	v_and_b32_e32 v25, 0xffff0000, v61
	v_fmac_f32_e32 v6, v78, v24
	v_fmac_f32_e32 v6, v79, v25
	v_lshlrev_b32_e32 v18, 16, v46
	v_and_b32_e32 v19, 0xffff0000, v46
	v_fmac_f32_e32 v2, v80, v18
	v_fmac_f32_e32 v2, v81, v19
	v_lshlrev_b32_e32 v20, 16, v62
	v_and_b32_e32 v21, 0xffff0000, v62
	v_fmac_f32_e32 v6, v80, v20
	v_fmac_f32_e32 v6, v81, v21
	v_lshlrev_b32_e32 v22, 16, v47
	v_and_b32_e32 v23, 0xffff0000, v47
	v_fmac_f32_e32 v2, v82, v22
	v_fmac_f32_e32 v2, v83, v23
	v_lshlrev_b32_e32 v24, 16, v63
	v_and_b32_e32 v25, 0xffff0000, v63
	v_fmac_f32_e32 v6, v82, v24
	v_fmac_f32_e32 v6, v83, v25
	v_lshlrev_b32_e32 v18, 16, v48
	v_and_b32_e32 v19, 0xffff0000, v48
	v_fmac_f32_e32 v2, v84, v18
	v_fmac_f32_e32 v2, v85, v19
	v_lshlrev_b32_e32 v20, 16, v64
	v_and_b32_e32 v21, 0xffff0000, v64
	v_fmac_f32_e32 v6, v84, v20
	v_fmac_f32_e32 v6, v85, v21
	v_lshlrev_b32_e32 v22, 16, v49
	v_and_b32_e32 v23, 0xffff0000, v49
	v_fmac_f32_e32 v2, v86, v22
	v_fmac_f32_e32 v2, v87, v23
	v_lshlrev_b32_e32 v24, 16, v65
	v_and_b32_e32 v25, 0xffff0000, v65
	v_fmac_f32_e32 v6, v86, v24
	v_fmac_f32_e32 v6, v87, v25
	v_lshlrev_b32_e32 v18, 16, v50
	v_and_b32_e32 v19, 0xffff0000, v50
	v_fmac_f32_e32 v2, v98, v18
	v_fmac_f32_e32 v2, v99, v19
	v_lshlrev_b32_e32 v20, 16, v66
	v_and_b32_e32 v21, 0xffff0000, v66
	v_fmac_f32_e32 v6, v98, v20
	v_fmac_f32_e32 v6, v99, v21
	v_lshlrev_b32_e32 v22, 16, v51
	v_and_b32_e32 v23, 0xffff0000, v51
	v_fmac_f32_e32 v2, v100, v22
	v_fmac_f32_e32 v2, v101, v23
	v_lshlrev_b32_e32 v24, 16, v67
	v_and_b32_e32 v25, 0xffff0000, v67
	v_fmac_f32_e32 v6, v100, v24
	v_fmac_f32_e32 v6, v101, v25
	v_lshlrev_b32_e32 v18, 16, v52
	v_and_b32_e32 v19, 0xffff0000, v52
	v_fmac_f32_e32 v2, v102, v18
	v_fmac_f32_e32 v2, v103, v19
	v_lshlrev_b32_e32 v20, 16, v68
	v_and_b32_e32 v21, 0xffff0000, v68
	v_fmac_f32_e32 v6, v102, v20
	v_fmac_f32_e32 v6, v103, v21
	v_lshlrev_b32_e32 v22, 16, v53
	v_and_b32_e32 v23, 0xffff0000, v53
	v_fmac_f32_e32 v2, v104, v22
	v_fmac_f32_e32 v2, v105, v23
	v_lshlrev_b32_e32 v24, 16, v69
	v_and_b32_e32 v25, 0xffff0000, v69
	v_fmac_f32_e32 v6, v104, v24
	v_fmac_f32_e32 v6, v105, v25
	v_lshlrev_b32_e32 v18, 16, v54
	v_and_b32_e32 v19, 0xffff0000, v54
	v_fmac_f32_e32 v2, v106, v18
	v_fmac_f32_e32 v2, v107, v19
	v_lshlrev_b32_e32 v20, 16, v70
	v_and_b32_e32 v21, 0xffff0000, v70
	v_fmac_f32_e32 v6, v106, v20
	v_fmac_f32_e32 v6, v107, v21
	v_lshlrev_b32_e32 v22, 16, v55
	v_and_b32_e32 v23, 0xffff0000, v55
	v_fmac_f32_e32 v2, v108, v22
	v_fmac_f32_e32 v2, v109, v23
	v_lshlrev_b32_e32 v24, 16, v71
	v_and_b32_e32 v25, 0xffff0000, v71
	v_fmac_f32_e32 v6, v108, v24
	v_fmac_f32_e32 v6, v109, v25
	v_lshlrev_b32_e32 v18, 16, v56
	v_and_b32_e32 v19, 0xffff0000, v56
	v_fmac_f32_e32 v2, v110, v18
	v_fmac_f32_e32 v2, v111, v19
	v_lshlrev_b32_e32 v20, 16, v72
	v_and_b32_e32 v21, 0xffff0000, v72
	v_fmac_f32_e32 v6, v110, v20
	v_fmac_f32_e32 v6, v111, v21
	v_lshlrev_b32_e32 v22, 16, v57
	v_and_b32_e32 v23, 0xffff0000, v57
	v_fmac_f32_e32 v2, v112, v22
	v_fmac_f32_e32 v2, v113, v23
	v_lshlrev_b32_e32 v24, 16, v73
	v_and_b32_e32 v25, 0xffff0000, v73
	v_fmac_f32_e32 v6, v112, v24
	v_fmac_f32_e32 v6, v113, v25
	v_lshlrev_b32_e32 v18, 16, v58
	v_and_b32_e32 v19, 0xffff0000, v58
	v_fmac_f32_e32 v2, v114, v18
	v_fmac_f32_e32 v2, v115, v19
	v_lshlrev_b32_e32 v20, 16, v74
	v_and_b32_e32 v21, 0xffff0000, v74
	v_fmac_f32_e32 v6, v114, v20
	v_fmac_f32_e32 v6, v115, v21
	v_lshlrev_b32_e32 v22, 16, v59
	v_and_b32_e32 v23, 0xffff0000, v59
	v_fmac_f32_e32 v2, v116, v22
	v_fmac_f32_e32 v2, v117, v23
	v_lshlrev_b32_e32 v24, 16, v75
	v_and_b32_e32 v25, 0xffff0000, v75
	v_fmac_f32_e32 v6, v116, v24
	v_fmac_f32_e32 v6, v117, v25
	s_add_u32 s100, s48, 0x12000
	s_addc_u32 s101, s49, 0
	global_load_dwordx4 v[76:79], v0, s[100:101]
	global_load_dwordx4 v[80:83], v0, s[100:101] offset:16
	global_load_dwordx4 v[84:87], v0, s[100:101] offset:2048
	global_load_dwordx4 v[98:101], v0, s[100:101] offset:2064
	global_load_dwordx4 v[102:105], v1, s[100:101]
	global_load_dwordx4 v[106:109], v1, s[100:101] offset:16
	global_load_dwordx4 v[110:113], v1, s[100:101] offset:2048
	global_load_dwordx4 v[114:117], v1, s[100:101] offset:2064
	s_waitcnt vmcnt(0)
; __device__ __forceinline__ void bias_phase(const bf16_t* W1T, const float* mod, float* cb, int gw, int NGW, int lane) {
;     ...
;         for (int b = 0; b < 4; ++b) { const float* sh = mod + (size_t)b * NMOD + 3 * DM; float s = 0.f;
; #pragma unroll
;             for (int j = 0; j < 4; ++j) { const f32x4 s0 = *(const f32x4*)(sh + (j * 64 + lane) * 8), s1 = *(const f32x4*)(sh + (j * 64 + lane) * 8 + 4);
;                 s += (w[8 * j + 0] * s0.x + w[8 * j + 1] * s0.y) + (w[8 * j + 2] * s0.z + w[8 * j + 3] * s0.w) + (w[8 * j + 4] * s1.x + w[8 * j + 5] * s1.y) + (w[8 * j + 6] * s1.z + w[8 * j + 7] * s1.w); }
	v_lshlrev_b32_e32 v18, 16, v44
	v_and_b32_e32 v19, 0xffff0000, v44
	v_fmac_f32_e32 v3, v76, v18
	v_fmac_f32_e32 v3, v77, v19
	v_lshlrev_b32_e32 v20, 16, v60
	v_and_b32_e32 v21, 0xffff0000, v60
	v_fmac_f32_e32 v7, v76, v20
	v_fmac_f32_e32 v7, v77, v21
	v_lshlrev_b32_e32 v22, 16, v45
	v_and_b32_e32 v23, 0xffff0000, v45
	v_fmac_f32_e32 v3, v78, v22
	v_fmac_f32_e32 v3, v79, v23
	v_lshlrev_b32_e32 v24, 16, v61
	v_and_b32_e32 v25, 0xffff0000, v61
	v_fmac_f32_e32 v7, v78, v24
	v_fmac_f32_e32 v7, v79, v25
	v_lshlrev_b32_e32 v18, 16, v46
	v_and_b32_e32 v19, 0xffff0000, v46
	v_fmac_f32_e32 v3, v80, v18
	v_fmac_f32_e32 v3, v81, v19
	v_lshlrev_b32_e32 v20, 16, v62
	v_and_b32_e32 v21, 0xffff0000, v62
	v_fmac_f32_e32 v7, v80, v20
	v_fmac_f32_e32 v7, v81, v21
	v_lshlrev_b32_e32 v22, 16, v47
	v_and_b32_e32 v23, 0xffff0000, v47
	v_fmac_f32_e32 v3, v82, v22
	v_fmac_f32_e32 v3, v83, v23
	v_lshlrev_b32_e32 v24, 16, v63
	v_and_b32_e32 v25, 0xffff0000, v63
	v_fmac_f32_e32 v7, v82, v24
	v_fmac_f32_e32 v7, v83, v25
	v_lshlrev_b32_e32 v18, 16, v48
	v_and_b32_e32 v19, 0xffff0000, v48
	v_fmac_f32_e32 v3, v84, v18
	v_fmac_f32_e32 v3, v85, v19
	v_lshlrev_b32_e32 v20, 16, v64
	v_and_b32_e32 v21, 0xffff0000, v64
	v_fmac_f32_e32 v7, v84, v20
	v_fmac_f32_e32 v7, v85, v21
	v_lshlrev_b32_e32 v22, 16, v49
	v_and_b32_e32 v23, 0xffff0000, v49
	v_fmac_f32_e32 v3, v86, v22
	v_fmac_f32_e32 v3, v87, v23
	v_lshlrev_b32_e32 v24, 16, v65
	v_and_b32_e32 v25, 0xffff0000, v65
	v_fmac_f32_e32 v7, v86, v24
	v_fmac_f32_e32 v7, v87, v25
	v_lshlrev_b32_e32 v18, 16, v50
	v_and_b32_e32 v19, 0xffff0000, v50
	v_fmac_f32_e32 v3, v98, v18
	v_fmac_f32_e32 v3, v99, v19
	v_lshlrev_b32_e32 v20, 16, v66
	v_and_b32_e32 v21, 0xffff0000, v66
	v_fmac_f32_e32 v7, v98, v20
	v_fmac_f32_e32 v7, v99, v21
	v_lshlrev_b32_e32 v22, 16, v51
	v_and_b32_e32 v23, 0xffff0000, v51
	v_fmac_f32_e32 v3, v100, v22
	v_fmac_f32_e32 v3, v101, v23
	v_lshlrev_b32_e32 v24, 16, v67
	v_and_b32_e32 v25, 0xffff0000, v67
	v_fmac_f32_e32 v7, v100, v24
	v_fmac_f32_e32 v7, v101, v25
	v_lshlrev_b32_e32 v18, 16, v52
	v_and_b32_e32 v19, 0xffff0000, v52
	v_fmac_f32_e32 v3, v102, v18
	v_fmac_f32_e32 v3, v103, v19
	v_lshlrev_b32_e32 v20, 16, v68
	v_and_b32_e32 v21, 0xffff0000, v68
	v_fmac_f32_e32 v7, v102, v20
	v_fmac_f32_e32 v7, v103, v21
	v_lshlrev_b32_e32 v22, 16, v53
	v_and_b32_e32 v23, 0xffff0000, v53
	v_fmac_f32_e32 v3, v104, v22
	v_fmac_f32_e32 v3, v105, v23
	v_lshlrev_b32_e32 v24, 16, v69
	v_and_b32_e32 v25, 0xffff0000, v69
	v_fmac_f32_e32 v7, v104, v24
	v_fmac_f32_e32 v7, v105, v25
	v_lshlrev_b32_e32 v18, 16, v54
	v_and_b32_e32 v19, 0xffff0000, v54
	v_fmac_f32_e32 v3, v106, v18
	v_fmac_f32_e32 v3, v107, v19
	v_lshlrev_b32_e32 v20, 16, v70
	v_and_b32_e32 v21, 0xffff0000, v70
	v_fmac_f32_e32 v7, v106, v20
	v_fmac_f32_e32 v7, v107, v21
	v_lshlrev_b32_e32 v22, 16, v55
	v_and_b32_e32 v23, 0xffff0000, v55
	v_fmac_f32_e32 v3, v108, v22
	v_fmac_f32_e32 v3, v109, v23
	v_lshlrev_b32_e32 v24, 16, v71
	v_and_b32_e32 v25, 0xffff0000, v71
	v_fmac_f32_e32 v7, v108, v24
	v_fmac_f32_e32 v7, v109, v25
	v_lshlrev_b32_e32 v18, 16, v56
	v_and_b32_e32 v19, 0xffff0000, v56
	v_fmac_f32_e32 v3, v110, v18
	v_fmac_f32_e32 v3, v111, v19
	v_lshlrev_b32_e32 v20, 16, v72
	v_and_b32_e32 v21, 0xffff0000, v72
	v_fmac_f32_e32 v7, v110, v20
	v_fmac_f32_e32 v7, v111, v21
	v_lshlrev_b32_e32 v22, 16, v57
	v_and_b32_e32 v23, 0xffff0000, v57
	v_fmac_f32_e32 v3, v112, v22
	v_fmac_f32_e32 v3, v113, v23
	v_lshlrev_b32_e32 v24, 16, v73
	v_and_b32_e32 v25, 0xffff0000, v73
	v_fmac_f32_e32 v7, v112, v24
	v_fmac_f32_e32 v7, v113, v25
	v_lshlrev_b32_e32 v18, 16, v58
	v_and_b32_e32 v19, 0xffff0000, v58
	v_fmac_f32_e32 v3, v114, v18
	v_fmac_f32_e32 v3, v115, v19
	v_lshlrev_b32_e32 v20, 16, v74
	v_and_b32_e32 v21, 0xffff0000, v74
	v_fmac_f32_e32 v7, v114, v20
	v_fmac_f32_e32 v7, v115, v21
	v_lshlrev_b32_e32 v22, 16, v59
	v_and_b32_e32 v23, 0xffff0000, v59
	v_fmac_f32_e32 v3, v116, v22
	v_fmac_f32_e32 v3, v117, v23
	v_lshlrev_b32_e32 v24, 16, v75
	v_and_b32_e32 v25, 0xffff0000, v75
	v_fmac_f32_e32 v7, v116, v24
	v_fmac_f32_e32 v7, v117, v25
	s_add_u32 s100, s48, 0x1e000
	s_addc_u32 s101, s49, 0
	global_load_dwordx4 v[76:79], v0, s[100:101]
	global_load_dwordx4 v[80:83], v0, s[100:101] offset:16
	global_load_dwordx4 v[84:87], v0, s[100:101] offset:2048
	global_load_dwordx4 v[98:101], v0, s[100:101] offset:2064
	global_load_dwordx4 v[102:105], v1, s[100:101]
	global_load_dwordx4 v[106:109], v1, s[100:101] offset:16
	global_load_dwordx4 v[110:113], v1, s[100:101] offset:2048
	global_load_dwordx4 v[114:117], v1, s[100:101] offset:2064
	s_waitcnt vmcnt(0)
; __device__ __forceinline__ void bias_phase(const bf16_t* W1T, const float* mod, float* cb, int gw, int NGW, int lane) {
;     ...
;         for (int b = 0; b < 4; ++b) { const float* sh = mod + (size_t)b * NMOD + 3 * DM; float s = 0.f;
; #pragma unroll
;             for (int j = 0; j < 4; ++j) { const f32x4 s0 = *(const f32x4*)(sh + (j * 64 + lane) * 8), s1 = *(const f32x4*)(sh + (j * 64 + lane) * 8 + 4);
;                 s += (w[8 * j + 0] * s0.x + w[8 * j + 1] * s0.y) + (w[8 * j + 2] * s0.z + w[8 * j + 3] * s0.w) + (w[8 * j + 4] * s1.x + w[8 * j + 5] * s1.y) + (w[8 * j + 6] * s1.z + w[8 * j + 7] * s1.w); }
	v_lshlrev_b32_e32 v18, 16, v44
	v_and_b32_e32 v19, 0xffff0000, v44
	v_fmac_f32_e32 v4, v76, v18
	v_fmac_f32_e32 v4, v77, v19
	v_lshlrev_b32_e32 v20, 16, v60
	v_and_b32_e32 v21, 0xffff0000, v60
	v_fmac_f32_e32 v8, v76, v20
	v_fmac_f32_e32 v8, v77, v21
	v_lshlrev_b32_e32 v22, 16, v45
	v_and_b32_e32 v23, 0xffff0000, v45
	v_fmac_f32_e32 v4, v78, v22
	v_fmac_f32_e32 v4, v79, v23
	v_lshlrev_b32_e32 v24, 16, v61
	v_and_b32_e32 v25, 0xffff0000, v61
	v_fmac_f32_e32 v8, v78, v24
	v_fmac_f32_e32 v8, v79, v25
	v_lshlrev_b32_e32 v18, 16, v46
	v_and_b32_e32 v19, 0xffff0000, v46
	v_fmac_f32_e32 v4, v80, v18
	v_fmac_f32_e32 v4, v81, v19
	v_lshlrev_b32_e32 v20, 16, v62
	v_and_b32_e32 v21, 0xffff0000, v62
	v_fmac_f32_e32 v8, v80, v20
	v_fmac_f32_e32 v8, v81, v21
	v_lshlrev_b32_e32 v22, 16, v47
	v_and_b32_e32 v23, 0xffff0000, v47
	v_fmac_f32_e32 v4, v82, v22
	v_fmac_f32_e32 v4, v83, v23
	v_lshlrev_b32_e32 v24, 16, v63
	v_and_b32_e32 v25, 0xffff0000, v63
	v_fmac_f32_e32 v8, v82, v24
	v_fmac_f32_e32 v8, v83, v25
	v_lshlrev_b32_e32 v18, 16, v48
	v_and_b32_e32 v19, 0xffff0000, v48
	v_fmac_f32_e32 v4, v84, v18
	v_fmac_f32_e32 v4, v85, v19
	v_lshlrev_b32_e32 v20, 16, v64
	v_and_b32_e32 v21, 0xffff0000, v64
	v_fmac_f32_e32 v8, v84, v20
	v_fmac_f32_e32 v8, v85, v21
	v_lshlrev_b32_e32 v22, 16, v49
	v_and_b32_e32 v23, 0xffff0000, v49
	v_fmac_f32_e32 v4, v86, v22
	v_fmac_f32_e32 v4, v87, v23
	v_lshlrev_b32_e32 v24, 16, v65
	v_and_b32_e32 v25, 0xffff0000, v65
	v_fmac_f32_e32 v8, v86, v24
	v_fmac_f32_e32 v8, v87, v25
	v_lshlrev_b32_e32 v18, 16, v50
	v_and_b32_e32 v19, 0xffff0000, v50
	v_fmac_f32_e32 v4, v98, v18
	v_fmac_f32_e32 v4, v99, v19
	v_lshlrev_b32_e32 v20, 16, v66
	v_and_b32_e32 v21, 0xffff0000, v66
	v_fmac_f32_e32 v8, v98, v20
	v_fmac_f32_e32 v8, v99, v21
	v_lshlrev_b32_e32 v22, 16, v51
	v_and_b32_e32 v23, 0xffff0000, v51
	v_fmac_f32_e32 v4, v100, v22
	v_fmac_f32_e32 v4, v101, v23
	v_lshlrev_b32_e32 v24, 16, v67
	v_and_b32_e32 v25, 0xffff0000, v67
	v_fmac_f32_e32 v8, v100, v24
	v_fmac_f32_e32 v8, v101, v25
	v_lshlrev_b32_e32 v18, 16, v52
	v_and_b32_e32 v19, 0xffff0000, v52
	v_fmac_f32_e32 v4, v102, v18
	v_fmac_f32_e32 v4, v103, v19
	v_lshlrev_b32_e32 v20, 16, v68
	v_and_b32_e32 v21, 0xffff0000, v68
	v_fmac_f32_e32 v8, v102, v20
	v_fmac_f32_e32 v8, v103, v21
	v_lshlrev_b32_e32 v22, 16, v53
	v_and_b32_e32 v23, 0xffff0000, v53
	v_fmac_f32_e32 v4, v104, v22
	v_fmac_f32_e32 v4, v105, v23
	v_lshlrev_b32_e32 v24, 16, v69
	v_and_b32_e32 v25, 0xffff0000, v69
	v_fmac_f32_e32 v8, v104, v24
	v_fmac_f32_e32 v8, v105, v25
	v_lshlrev_b32_e32 v18, 16, v54
	v_and_b32_e32 v19, 0xffff0000, v54
	v_fmac_f32_e32 v4, v106, v18
	v_fmac_f32_e32 v4, v107, v19
	v_lshlrev_b32_e32 v20, 16, v70
	v_and_b32_e32 v21, 0xffff0000, v70
	v_fmac_f32_e32 v8, v106, v20
	v_fmac_f32_e32 v8, v107, v21
	v_lshlrev_b32_e32 v22, 16, v55
	v_and_b32_e32 v23, 0xffff0000, v55
	v_fmac_f32_e32 v4, v108, v22
	v_fmac_f32_e32 v4, v109, v23
	v_lshlrev_b32_e32 v24, 16, v71
	v_and_b32_e32 v25, 0xffff0000, v71
	v_fmac_f32_e32 v8, v108, v24
	v_fmac_f32_e32 v8, v109, v25
	v_lshlrev_b32_e32 v18, 16, v56
	v_and_b32_e32 v19, 0xffff0000, v56
	v_fmac_f32_e32 v4, v110, v18
	v_fmac_f32_e32 v4, v111, v19
	v_lshlrev_b32_e32 v20, 16, v72
	v_and_b32_e32 v21, 0xffff0000, v72
	v_fmac_f32_e32 v8, v110, v20
	v_fmac_f32_e32 v8, v111, v21
	v_lshlrev_b32_e32 v22, 16, v57
	v_and_b32_e32 v23, 0xffff0000, v57
	v_fmac_f32_e32 v4, v112, v22
	v_fmac_f32_e32 v4, v113, v23
	v_lshlrev_b32_e32 v24, 16, v73
	v_and_b32_e32 v25, 0xffff0000, v73
	v_fmac_f32_e32 v8, v112, v24
	v_fmac_f32_e32 v8, v113, v25
	v_lshlrev_b32_e32 v18, 16, v58
	v_and_b32_e32 v19, 0xffff0000, v58
	v_fmac_f32_e32 v4, v114, v18
	v_fmac_f32_e32 v4, v115, v19
	v_lshlrev_b32_e32 v20, 16, v74
	v_and_b32_e32 v21, 0xffff0000, v74
	v_fmac_f32_e32 v8, v114, v20
	v_fmac_f32_e32 v8, v115, v21
	v_lshlrev_b32_e32 v22, 16, v59
	v_and_b32_e32 v23, 0xffff0000, v59
	v_fmac_f32_e32 v4, v116, v22
	v_fmac_f32_e32 v4, v117, v23
	v_lshlrev_b32_e32 v24, 16, v75
	v_and_b32_e32 v25, 0xffff0000, v75
	v_fmac_f32_e32 v8, v116, v24
	v_fmac_f32_e32 v8, v117, v25
	s_add_u32 s100, s48, 0x2a000
	s_addc_u32 s101, s49, 0
	global_load_dwordx4 v[76:79], v0, s[100:101]
	global_load_dwordx4 v[80:83], v0, s[100:101] offset:16
	global_load_dwordx4 v[84:87], v0, s[100:101] offset:2048
	global_load_dwordx4 v[98:101], v0, s[100:101] offset:2064
	global_load_dwordx4 v[102:105], v1, s[100:101]
	global_load_dwordx4 v[106:109], v1, s[100:101] offset:16
	global_load_dwordx4 v[110:113], v1, s[100:101] offset:2048
	global_load_dwordx4 v[114:117], v1, s[100:101] offset:2064
	s_waitcnt vmcnt(0)
; __device__ __forceinline__ float bflo(unsigned w) { return __uint_as_float(w << 16); }
; __device__ __forceinline__ float bfhi(unsigned w) { return __uint_as_float(w & 0xffff0000u); }
; __device__ __forceinline__ void bias_phase(const bf16_t* W1T, const float* mod, float* cb, int gw, int NGW, int lane) {
;     ...
;         for (int j = 0; j < 4; ++j) { const u32x4 r = *(const u32x4*)(W1T + (size_t)n * DM + (j * 64 + lane) * 8);
;             w[8 * j + 0] = bflo(r.x); w[8 * j + 1] = bfhi(r.x); w[8 * j + 2] = bflo(r.y); w[8 * j + 3] = bfhi(r.y); w[8 * j + 4] = bflo(r.z); w[8 * j + 5] = bfhi(r.z); w[8 * j + 6] = bflo(r.w); w[8 * j + 7] = bfhi(r.w); }
; #pragma unroll
;         for (int b = 0; b < 4; ++b) { const float* sh = mod + (size_t)b * NMOD + 3 * DM; float s = 0.f;
; #pragma unroll
;             for (int j = 0; j < 4; ++j) { const f32x4 s0 = *(const f32x4*)(sh + (j * 64 + lane) * 8), s1 = *(const f32x4*)(sh + (j * 64 + lane) * 8 + 4);
;                 s += (w[8 * j + 0] * s0.x + w[8 * j + 1] * s0.y) + (w[8 * j + 2] * s0.z + w[8 * j + 3] * s0.w) + (w[8 * j + 4] * s1.x + w[8 * j + 5] * s1.y) + (w[8 * j + 6] * s1.z + w[8 * j + 7] * s1.w); }
	v_lshlrev_b32_e32 v18, 16, v44
	v_and_b32_e32 v19, 0xffff0000, v44
	v_fmac_f32_e32 v5, v76, v18
	v_fmac_f32_e32 v5, v77, v19
	v_lshlrev_b32_e32 v20, 16, v60
	v_and_b32_e32 v21, 0xffff0000, v60
	v_fmac_f32_e32 v9, v76, v20
	v_fmac_f32_e32 v9, v77, v21
	v_lshlrev_b32_e32 v22, 16, v45
	v_and_b32_e32 v23, 0xffff0000, v45
	v_fmac_f32_e32 v5, v78, v22
	v_fmac_f32_e32 v5, v79, v23
	v_lshlrev_b32_e32 v24, 16, v61
	v_and_b32_e32 v25, 0xffff0000, v61
	v_fmac_f32_e32 v9, v78, v24
	v_fmac_f32_e32 v9, v79, v25
	v_lshlrev_b32_e32 v18, 16, v46
	v_and_b32_e32 v19, 0xffff0000, v46
	v_fmac_f32_e32 v5, v80, v18
	v_fmac_f32_e32 v5, v81, v19
	v_lshlrev_b32_e32 v20, 16, v62
	v_and_b32_e32 v21, 0xffff0000, v62
	v_fmac_f32_e32 v9, v80, v20
	v_fmac_f32_e32 v9, v81, v21
	v_lshlrev_b32_e32 v22, 16, v47
	v_and_b32_e32 v23, 0xffff0000, v47
	v_fmac_f32_e32 v5, v82, v22
	v_fmac_f32_e32 v5, v83, v23
	v_lshlrev_b32_e32 v24, 16, v63
	v_and_b32_e32 v25, 0xffff0000, v63
	v_fmac_f32_e32 v9, v82, v24
	v_fmac_f32_e32 v9, v83, v25
	v_lshlrev_b32_e32 v18, 16, v48
	v_and_b32_e32 v19, 0xffff0000, v48
	v_fmac_f32_e32 v5, v84, v18
	v_fmac_f32_e32 v5, v85, v19
	v_lshlrev_b32_e32 v20, 16, v64
	v_and_b32_e32 v21, 0xffff0000, v64
	v_fmac_f32_e32 v9, v84, v20
	v_fmac_f32_e32 v9, v85, v21
	v_lshlrev_b32_e32 v22, 16, v49
	v_and_b32_e32 v23, 0xffff0000, v49
	v_fmac_f32_e32 v5, v86, v22
	v_fmac_f32_e32 v5, v87, v23
	v_lshlrev_b32_e32 v24, 16, v65
	v_and_b32_e32 v25, 0xffff0000, v65
	v_fmac_f32_e32 v9, v86, v24
	v_fmac_f32_e32 v9, v87, v25
	v_lshlrev_b32_e32 v18, 16, v50
	v_and_b32_e32 v19, 0xffff0000, v50
	v_fmac_f32_e32 v5, v98, v18
	v_fmac_f32_e32 v5, v99, v19
	v_lshlrev_b32_e32 v20, 16, v66
	v_and_b32_e32 v21, 0xffff0000, v66
	v_fmac_f32_e32 v9, v98, v20
	v_fmac_f32_e32 v9, v99, v21
	v_lshlrev_b32_e32 v22, 16, v51
	v_and_b32_e32 v23, 0xffff0000, v51
	v_fmac_f32_e32 v5, v100, v22
	v_fmac_f32_e32 v5, v101, v23
	v_lshlrev_b32_e32 v24, 16, v67
	v_and_b32_e32 v25, 0xffff0000, v67
	v_fmac_f32_e32 v9, v100, v24
	v_fmac_f32_e32 v9, v101, v25
	v_lshlrev_b32_e32 v18, 16, v52
	v_and_b32_e32 v19, 0xffff0000, v52
	v_fmac_f32_e32 v5, v102, v18
	v_fmac_f32_e32 v5, v103, v19
	v_lshlrev_b32_e32 v20, 16, v68
	v_and_b32_e32 v21, 0xffff0000, v68
	v_fmac_f32_e32 v9, v102, v20
	v_fmac_f32_e32 v9, v103, v21
	v_lshlrev_b32_e32 v22, 16, v53
	v_and_b32_e32 v23, 0xffff0000, v53
	v_fmac_f32_e32 v5, v104, v22
	v_fmac_f32_e32 v5, v105, v23
	v_lshlrev_b32_e32 v24, 16, v69
	v_and_b32_e32 v25, 0xffff0000, v69
	v_fmac_f32_e32 v9, v104, v24
	v_fmac_f32_e32 v9, v105, v25
	v_lshlrev_b32_e32 v18, 16, v54
	v_and_b32_e32 v19, 0xffff0000, v54
	v_fmac_f32_e32 v5, v106, v18
	v_fmac_f32_e32 v5, v107, v19
	v_lshlrev_b32_e32 v20, 16, v70
	v_and_b32_e32 v21, 0xffff0000, v70
	v_fmac_f32_e32 v9, v106, v20
	v_fmac_f32_e32 v9, v107, v21
	v_lshlrev_b32_e32 v22, 16, v55
	v_and_b32_e32 v23, 0xffff0000, v55
	v_fmac_f32_e32 v5, v108, v22
	v_fmac_f32_e32 v5, v109, v23
	v_lshlrev_b32_e32 v24, 16, v71
	v_and_b32_e32 v25, 0xffff0000, v71
	v_fmac_f32_e32 v9, v108, v24
	v_fmac_f32_e32 v9, v109, v25
	v_lshlrev_b32_e32 v18, 16, v56
	v_and_b32_e32 v19, 0xffff0000, v56
	v_fmac_f32_e32 v5, v110, v18
	v_fmac_f32_e32 v5, v111, v19
	v_lshlrev_b32_e32 v20, 16, v72
	v_and_b32_e32 v21, 0xffff0000, v72
	v_fmac_f32_e32 v9, v110, v20
	v_fmac_f32_e32 v9, v111, v21
	v_lshlrev_b32_e32 v22, 16, v57
	v_and_b32_e32 v23, 0xffff0000, v57
	v_fmac_f32_e32 v5, v112, v22
	v_fmac_f32_e32 v5, v113, v23
	v_lshlrev_b32_e32 v24, 16, v73
	v_and_b32_e32 v25, 0xffff0000, v73
	v_fmac_f32_e32 v9, v112, v24
	v_fmac_f32_e32 v9, v113, v25
	v_lshlrev_b32_e32 v18, 16, v58
	v_and_b32_e32 v19, 0xffff0000, v58
	v_fmac_f32_e32 v5, v114, v18
	v_fmac_f32_e32 v5, v115, v19
	v_lshlrev_b32_e32 v20, 16, v74
	v_and_b32_e32 v21, 0xffff0000, v74
	v_fmac_f32_e32 v9, v114, v20
	v_fmac_f32_e32 v9, v115, v21
	v_lshlrev_b32_e32 v22, 16, v59
	v_and_b32_e32 v23, 0xffff0000, v59
	v_fmac_f32_e32 v5, v116, v22
	v_fmac_f32_e32 v5, v117, v23
	v_lshlrev_b32_e32 v24, 16, v75
	v_and_b32_e32 v25, 0xffff0000, v75
	v_fmac_f32_e32 v9, v116, v24
	v_fmac_f32_e32 v9, v117, v25
	s_mul_i32 s10, s6, 2
	v_add_u32_e32 v26, s10, v32
	s_mul_i32 s10, s6, 3
	v_add_u32_e32 v27, s10, v32
	global_load_dwordx4 v[44:47], v26, s[98:99]
	global_load_dwordx4 v[48:51], v26, s[98:99] offset:1024
	global_load_dwordx4 v[52:55], v26, s[98:99] offset:2048
	global_load_dwordx4 v[56:59], v26, s[98:99] offset:3072
	global_load_dwordx4 v[60:63], v27, s[98:99]
	global_load_dwordx4 v[64:67], v27, s[98:99] offset:1024
	global_load_dwordx4 v[68:71], v27, s[98:99] offset:2048
	global_load_dwordx4 v[72:75], v27, s[98:99] offset:3072
	s_add_u32 s100, s48, 0x6000
	s_addc_u32 s101, s49, 0
	global_load_dwordx4 v[76:79], v0, s[100:101]
	global_load_dwordx4 v[80:83], v0, s[100:101] offset:16
	global_load_dwordx4 v[84:87], v0, s[100:101] offset:2048
	global_load_dwordx4 v[98:101], v0, s[100:101] offset:2064
	global_load_dwordx4 v[102:105], v1, s[100:101]
	global_load_dwordx4 v[106:109], v1, s[100:101] offset:16
	global_load_dwordx4 v[110:113], v1, s[100:101] offset:2048
	global_load_dwordx4 v[114:117], v1, s[100:101] offset:2064
	s_waitcnt vmcnt(0)
; __device__ __forceinline__ float bflo(unsigned w) { return __uint_as_float(w << 16); }
; __device__ __forceinline__ float bfhi(unsigned w) { return __uint_as_float(w & 0xffff0000u); }
; __device__ __forceinline__ void bias_phase(const bf16_t* W1T, const float* mod, float* cb, int gw, int NGW, int lane) {
;     for (int n = gw; n < HID; n += NGW) {
;         float w[32];
; #pragma unroll
;         for (int j = 0; j < 4; ++j) { const u32x4 r = *(const u32x4*)(W1T + (size_t)n * DM + (j * 64 + lane) * 8);
;             w[8 * j + 0] = bflo(r.x); w[8 * j + 1] = bfhi(r.x); w[8 * j + 2] = bflo(r.y); w[8 * j + 3] = bfhi(r.y); w[8 * j + 4] = bflo(r.z); w[8 * j + 5] = bfhi(r.z); w[8 * j + 6] = bflo(r.w); w[8 * j + 7] = bfhi(r.w); }
; #pragma unroll
;         for (int b = 0; b < 4; ++b) { const float* sh = mod + (size_t)b * NMOD + 3 * DM; float s = 0.f;
; #pragma unroll
;             for (int j = 0; j < 4; ++j) { const f32x4 s0 = *(const f32x4*)(sh + (j * 64 + lane) * 8), s1 = *(const f32x4*)(sh + (j * 64 + lane) * 8 + 4);
;                 s += (w[8 * j + 0] * s0.x + w[8 * j + 1] * s0.y) + (w[8 * j + 2] * s0.z + w[8 * j + 3] * s0.w) + (w[8 * j + 4] * s1.x + w[8 * j + 5] * s1.y) + (w[8 * j + 6] * s1.z + w[8 * j + 7] * s1.w); }
	v_lshlrev_b32_e32 v18, 16, v44
	v_and_b32_e32 v19, 0xffff0000, v44
	v_fmac_f32_e32 v10, v76, v18
	v_fmac_f32_e32 v10, v77, v19
	v_lshlrev_b32_e32 v20, 16, v60
	v_and_b32_e32 v21, 0xffff0000, v60
	v_fmac_f32_e32 v14, v76, v20
	v_fmac_f32_e32 v14, v77, v21
	v_lshlrev_b32_e32 v22, 16, v45
	v_and_b32_e32 v23, 0xffff0000, v45
	v_fmac_f32_e32 v10, v78, v22
	v_fmac_f32_e32 v10, v79, v23
	v_lshlrev_b32_e32 v24, 16, v61
	v_and_b32_e32 v25, 0xffff0000, v61
	v_fmac_f32_e32 v14, v78, v24
	v_fmac_f32_e32 v14, v79, v25
	v_lshlrev_b32_e32 v18, 16, v46
	v_and_b32_e32 v19, 0xffff0000, v46
	v_fmac_f32_e32 v10, v80, v18
	v_fmac_f32_e32 v10, v81, v19
	v_lshlrev_b32_e32 v20, 16, v62
	v_and_b32_e32 v21, 0xffff0000, v62
	v_fmac_f32_e32 v14, v80, v20
	v_fmac_f32_e32 v14, v81, v21
	v_lshlrev_b32_e32 v22, 16, v47
	v_and_b32_e32 v23, 0xffff0000, v47
	v_fmac_f32_e32 v10, v82, v22
	v_fmac_f32_e32 v10, v83, v23
	v_lshlrev_b32_e32 v24, 16, v63
	v_and_b32_e32 v25, 0xffff0000, v63
	v_fmac_f32_e32 v14, v82, v24
	v_fmac_f32_e32 v14, v83, v25
	v_lshlrev_b32_e32 v18, 16, v48
	v_and_b32_e32 v19, 0xffff0000, v48
	v_fmac_f32_e32 v10, v84, v18
	v_fmac_f32_e32 v10, v85, v19
	v_lshlrev_b32_e32 v20, 16, v64
	v_and_b32_e32 v21, 0xffff0000, v64
	v_fmac_f32_e32 v14, v84, v20
	v_fmac_f32_e32 v14, v85, v21
	v_lshlrev_b32_e32 v22, 16, v49
	v_and_b32_e32 v23, 0xffff0000, v49
	v_fmac_f32_e32 v10, v86, v22
	v_fmac_f32_e32 v10, v87, v23
	v_lshlrev_b32_e32 v24, 16, v65
	v_and_b32_e32 v25, 0xffff0000, v65
	v_fmac_f32_e32 v14, v86, v24
	v_fmac_f32_e32 v14, v87, v25
	v_lshlrev_b32_e32 v18, 16, v50
	v_and_b32_e32 v19, 0xffff0000, v50
	v_fmac_f32_e32 v10, v98, v18
	v_fmac_f32_e32 v10, v99, v19
	v_lshlrev_b32_e32 v20, 16, v66
	v_and_b32_e32 v21, 0xffff0000, v66
	v_fmac_f32_e32 v14, v98, v20
	v_fmac_f32_e32 v14, v99, v21
	v_lshlrev_b32_e32 v22, 16, v51
	v_and_b32_e32 v23, 0xffff0000, v51
	v_fmac_f32_e32 v10, v100, v22
	v_fmac_f32_e32 v10, v101, v23
	v_lshlrev_b32_e32 v24, 16, v67
	v_and_b32_e32 v25, 0xffff0000, v67
	v_fmac_f32_e32 v14, v100, v24
	v_fmac_f32_e32 v14, v101, v25
	v_lshlrev_b32_e32 v18, 16, v52
	v_and_b32_e32 v19, 0xffff0000, v52
	v_fmac_f32_e32 v10, v102, v18
	v_fmac_f32_e32 v10, v103, v19
	v_lshlrev_b32_e32 v20, 16, v68
	v_and_b32_e32 v21, 0xffff0000, v68
	v_fmac_f32_e32 v14, v102, v20
	v_fmac_f32_e32 v14, v103, v21
	v_lshlrev_b32_e32 v22, 16, v53
	v_and_b32_e32 v23, 0xffff0000, v53
	v_fmac_f32_e32 v10, v104, v22
	v_fmac_f32_e32 v10, v105, v23
	v_lshlrev_b32_e32 v24, 16, v69
	v_and_b32_e32 v25, 0xffff0000, v69
	v_fmac_f32_e32 v14, v104, v24
	v_fmac_f32_e32 v14, v105, v25
	v_lshlrev_b32_e32 v18, 16, v54
	v_and_b32_e32 v19, 0xffff0000, v54
	v_fmac_f32_e32 v10, v106, v18
	v_fmac_f32_e32 v10, v107, v19
	v_lshlrev_b32_e32 v20, 16, v70
	v_and_b32_e32 v21, 0xffff0000, v70
	v_fmac_f32_e32 v14, v106, v20
	v_fmac_f32_e32 v14, v107, v21
	v_lshlrev_b32_e32 v22, 16, v55
	v_and_b32_e32 v23, 0xffff0000, v55
	v_fmac_f32_e32 v10, v108, v22
	v_fmac_f32_e32 v10, v109, v23
	v_lshlrev_b32_e32 v24, 16, v71
	v_and_b32_e32 v25, 0xffff0000, v71
	v_fmac_f32_e32 v14, v108, v24
	v_fmac_f32_e32 v14, v109, v25
	v_lshlrev_b32_e32 v18, 16, v56
	v_and_b32_e32 v19, 0xffff0000, v56
	v_fmac_f32_e32 v10, v110, v18
	v_fmac_f32_e32 v10, v111, v19
	v_lshlrev_b32_e32 v20, 16, v72
	v_and_b32_e32 v21, 0xffff0000, v72
	v_fmac_f32_e32 v14, v110, v20
	v_fmac_f32_e32 v14, v111, v21
	v_lshlrev_b32_e32 v22, 16, v57
	v_and_b32_e32 v23, 0xffff0000, v57
	v_fmac_f32_e32 v10, v112, v22
	v_fmac_f32_e32 v10, v113, v23
	v_lshlrev_b32_e32 v24, 16, v73
	v_and_b32_e32 v25, 0xffff0000, v73
	v_fmac_f32_e32 v14, v112, v24
	v_fmac_f32_e32 v14, v113, v25
	v_lshlrev_b32_e32 v18, 16, v58
	v_and_b32_e32 v19, 0xffff0000, v58
	v_fmac_f32_e32 v10, v114, v18
	v_fmac_f32_e32 v10, v115, v19
	v_lshlrev_b32_e32 v20, 16, v74
	v_and_b32_e32 v21, 0xffff0000, v74
	v_fmac_f32_e32 v14, v114, v20
	v_fmac_f32_e32 v14, v115, v21
	v_lshlrev_b32_e32 v22, 16, v59
	v_and_b32_e32 v23, 0xffff0000, v59
	v_fmac_f32_e32 v10, v116, v22
	v_fmac_f32_e32 v10, v117, v23
	v_lshlrev_b32_e32 v24, 16, v75
	v_and_b32_e32 v25, 0xffff0000, v75
	v_fmac_f32_e32 v14, v116, v24
	v_fmac_f32_e32 v14, v117, v25
	s_add_u32 s100, s48, 0x12000
	s_addc_u32 s101, s49, 0
	global_load_dwordx4 v[76:79], v0, s[100:101]
	global_load_dwordx4 v[80:83], v0, s[100:101] offset:16
	global_load_dwordx4 v[84:87], v0, s[100:101] offset:2048
	global_load_dwordx4 v[98:101], v0, s[100:101] offset:2064
	global_load_dwordx4 v[102:105], v1, s[100:101]
	global_load_dwordx4 v[106:109], v1, s[100:101] offset:16
	global_load_dwordx4 v[110:113], v1, s[100:101] offset:2048
	global_load_dwordx4 v[114:117], v1, s[100:101] offset:2064
	s_waitcnt vmcnt(0)
; __device__ __forceinline__ float bflo(unsigned w) { return __uint_as_float(w << 16); }
; __device__ __forceinline__ float bfhi(unsigned w) { return __uint_as_float(w & 0xffff0000u); }
; __device__ __forceinline__ void bias_phase(const bf16_t* W1T, const float* mod, float* cb, int gw, int NGW, int lane) {
;     for (int n = gw; n < HID; n += NGW) {
;         float w[32];
; #pragma unroll
;         for (int j = 0; j < 4; ++j) { const u32x4 r = *(const u32x4*)(W1T + (size_t)n * DM + (j * 64 + lane) * 8);
;             w[8 * j + 0] = bflo(r.x); w[8 * j + 1] = bfhi(r.x); w[8 * j + 2] = bflo(r.y); w[8 * j + 3] = bfhi(r.y); w[8 * j + 4] = bflo(r.z); w[8 * j + 5] = bfhi(r.z); w[8 * j + 6] = bflo(r.w); w[8 * j + 7] = bfhi(r.w); }
; #pragma unroll
;         for (int b = 0; b < 4; ++b) { const float* sh = mod + (size_t)b * NMOD + 3 * DM; float s = 0.f;
; #pragma unroll
;             for (int j = 0; j < 4; ++j) { const f32x4 s0 = *(const f32x4*)(sh + (j * 64 + lane) * 8), s1 = *(const f32x4*)(sh + (j * 64 + lane) * 8 + 4);
;                 s += (w[8 * j + 0] * s0.x + w[8 * j + 1] * s0.y) + (w[8 * j + 2] * s0.z + w[8 * j + 3] * s0.w) + (w[8 * j + 4] * s1.x + w[8 * j + 5] * s1.y) + (w[8 * j + 6] * s1.z + w[8 * j + 7] * s1.w); }
	v_lshlrev_b32_e32 v18, 16, v44
	v_and_b32_e32 v19, 0xffff0000, v44
	v_fmac_f32_e32 v11, v76, v18
	v_fmac_f32_e32 v11, v77, v19
	v_lshlrev_b32_e32 v20, 16, v60
	v_and_b32_e32 v21, 0xffff0000, v60
	v_fmac_f32_e32 v15, v76, v20
	v_fmac_f32_e32 v15, v77, v21
	v_lshlrev_b32_e32 v22, 16, v45
	v_and_b32_e32 v23, 0xffff0000, v45
	v_fmac_f32_e32 v11, v78, v22
	v_fmac_f32_e32 v11, v79, v23
	v_lshlrev_b32_e32 v24, 16, v61
	v_and_b32_e32 v25, 0xffff0000, v61
	v_fmac_f32_e32 v15, v78, v24
	v_fmac_f32_e32 v15, v79, v25
	v_lshlrev_b32_e32 v18, 16, v46
	v_and_b32_e32 v19, 0xffff0000, v46
	v_fmac_f32_e32 v11, v80, v18
	v_fmac_f32_e32 v11, v81, v19
	v_lshlrev_b32_e32 v20, 16, v62
	v_and_b32_e32 v21, 0xffff0000, v62
	v_fmac_f32_e32 v15, v80, v20
	v_fmac_f32_e32 v15, v81, v21
	v_lshlrev_b32_e32 v22, 16, v47
	v_and_b32_e32 v23, 0xffff0000, v47
	v_fmac_f32_e32 v11, v82, v22
	v_fmac_f32_e32 v11, v83, v23
	v_lshlrev_b32_e32 v24, 16, v63
	v_and_b32_e32 v25, 0xffff0000, v63
	v_fmac_f32_e32 v15, v82, v24
	v_fmac_f32_e32 v15, v83, v25
	v_lshlrev_b32_e32 v18, 16, v48
	v_and_b32_e32 v19, 0xffff0000, v48
	v_fmac_f32_e32 v11, v84, v18
	v_fmac_f32_e32 v11, v85, v19
	v_lshlrev_b32_e32 v20, 16, v64
	v_and_b32_e32 v21, 0xffff0000, v64
	v_fmac_f32_e32 v15, v84, v20
	v_fmac_f32_e32 v15, v85, v21
	v_lshlrev_b32_e32 v22, 16, v49
	v_and_b32_e32 v23, 0xffff0000, v49
	v_fmac_f32_e32 v11, v86, v22
	v_fmac_f32_e32 v11, v87, v23
	v_lshlrev_b32_e32 v24, 16, v65
	v_and_b32_e32 v25, 0xffff0000, v65
	v_fmac_f32_e32 v15, v86, v24
	v_fmac_f32_e32 v15, v87, v25
	v_lshlrev_b32_e32 v18, 16, v50
	v_and_b32_e32 v19, 0xffff0000, v50
	v_fmac_f32_e32 v11, v98, v18
	v_fmac_f32_e32 v11, v99, v19
	v_lshlrev_b32_e32 v20, 16, v66
	v_and_b32_e32 v21, 0xffff0000, v66
	v_fmac_f32_e32 v15, v98, v20
	v_fmac_f32_e32 v15, v99, v21
	v_lshlrev_b32_e32 v22, 16, v51
	v_and_b32_e32 v23, 0xffff0000, v51
	v_fmac_f32_e32 v11, v100, v22
	v_fmac_f32_e32 v11, v101, v23
	v_lshlrev_b32_e32 v24, 16, v67
	v_and_b32_e32 v25, 0xffff0000, v67
	v_fmac_f32_e32 v15, v100, v24
	v_fmac_f32_e32 v15, v101, v25
	v_lshlrev_b32_e32 v18, 16, v52
	v_and_b32_e32 v19, 0xffff0000, v52
	v_fmac_f32_e32 v11, v102, v18
	v_fmac_f32_e32 v11, v103, v19
	v_lshlrev_b32_e32 v20, 16, v68
	v_and_b32_e32 v21, 0xffff0000, v68
	v_fmac_f32_e32 v15, v102, v20
	v_fmac_f32_e32 v15, v103, v21
	v_lshlrev_b32_e32 v22, 16, v53
	v_and_b32_e32 v23, 0xffff0000, v53
	v_fmac_f32_e32 v11, v104, v22
	v_fmac_f32_e32 v11, v105, v23
	v_lshlrev_b32_e32 v24, 16, v69
	v_and_b32_e32 v25, 0xffff0000, v69
	v_fmac_f32_e32 v15, v104, v24
	v_fmac_f32_e32 v15, v105, v25
	v_lshlrev_b32_e32 v18, 16, v54
	v_and_b32_e32 v19, 0xffff0000, v54
	v_fmac_f32_e32 v11, v106, v18
	v_fmac_f32_e32 v11, v107, v19
	v_lshlrev_b32_e32 v20, 16, v70
	v_and_b32_e32 v21, 0xffff0000, v70
	v_fmac_f32_e32 v15, v106, v20
	v_fmac_f32_e32 v15, v107, v21
	v_lshlrev_b32_e32 v22, 16, v55
	v_and_b32_e32 v23, 0xffff0000, v55
	v_fmac_f32_e32 v11, v108, v22
	v_fmac_f32_e32 v11, v109, v23
	v_lshlrev_b32_e32 v24, 16, v71
	v_and_b32_e32 v25, 0xffff0000, v71
	v_fmac_f32_e32 v15, v108, v24
	v_fmac_f32_e32 v15, v109, v25
	v_lshlrev_b32_e32 v18, 16, v56
	v_and_b32_e32 v19, 0xffff0000, v56
	v_fmac_f32_e32 v11, v110, v18
	v_fmac_f32_e32 v11, v111, v19
	v_lshlrev_b32_e32 v20, 16, v72
	v_and_b32_e32 v21, 0xffff0000, v72
	v_fmac_f32_e32 v15, v110, v20
	v_fmac_f32_e32 v15, v111, v21
	v_lshlrev_b32_e32 v22, 16, v57
	v_and_b32_e32 v23, 0xffff0000, v57
	v_fmac_f32_e32 v11, v112, v22
	v_fmac_f32_e32 v11, v113, v23
	v_lshlrev_b32_e32 v24, 16, v73
	v_and_b32_e32 v25, 0xffff0000, v73
	v_fmac_f32_e32 v15, v112, v24
	v_fmac_f32_e32 v15, v113, v25
	v_lshlrev_b32_e32 v18, 16, v58
	v_and_b32_e32 v19, 0xffff0000, v58
	v_fmac_f32_e32 v11, v114, v18
	v_fmac_f32_e32 v11, v115, v19
	v_lshlrev_b32_e32 v20, 16, v74
	v_and_b32_e32 v21, 0xffff0000, v74
	v_fmac_f32_e32 v15, v114, v20
	v_fmac_f32_e32 v15, v115, v21
	v_lshlrev_b32_e32 v22, 16, v59
	v_and_b32_e32 v23, 0xffff0000, v59
	v_fmac_f32_e32 v11, v116, v22
	v_fmac_f32_e32 v11, v117, v23
	v_lshlrev_b32_e32 v24, 16, v75
	v_and_b32_e32 v25, 0xffff0000, v75
	v_fmac_f32_e32 v15, v116, v24
	v_fmac_f32_e32 v15, v117, v25
	s_add_u32 s100, s48, 0x1e000
	s_addc_u32 s101, s49, 0
	global_load_dwordx4 v[76:79], v0, s[100:101]
	global_load_dwordx4 v[80:83], v0, s[100:101] offset:16
	global_load_dwordx4 v[84:87], v0, s[100:101] offset:2048
	global_load_dwordx4 v[98:101], v0, s[100:101] offset:2064
	global_load_dwordx4 v[102:105], v1, s[100:101]
	global_load_dwordx4 v[106:109], v1, s[100:101] offset:16
	global_load_dwordx4 v[110:113], v1, s[100:101] offset:2048
	global_load_dwordx4 v[114:117], v1, s[100:101] offset:2064
	s_waitcnt vmcnt(0)
; __device__ __forceinline__ float bflo(unsigned w) { return __uint_as_float(w << 16); }
; __device__ __forceinline__ float bfhi(unsigned w) { return __uint_as_float(w & 0xffff0000u); }
; __device__ __forceinline__ void bias_phase(const bf16_t* W1T, const float* mod, float* cb, int gw, int NGW, int lane) {
;     for (int n = gw; n < HID; n += NGW) {
;         float w[32];
; #pragma unroll
;         for (int j = 0; j < 4; ++j) { const u32x4 r = *(const u32x4*)(W1T + (size_t)n * DM + (j * 64 + lane) * 8);
;             w[8 * j + 0] = bflo(r.x); w[8 * j + 1] = bfhi(r.x); w[8 * j + 2] = bflo(r.y); w[8 * j + 3] = bfhi(r.y); w[8 * j + 4] = bflo(r.z); w[8 * j + 5] = bfhi(r.z); w[8 * j + 6] = bflo(r.w); w[8 * j + 7] = bfhi(r.w); }
; #pragma unroll
;         for (int b = 0; b < 4; ++b) { const float* sh = mod + (size_t)b * NMOD + 3 * DM; float s = 0.f;
; #pragma unroll
;             for (int j = 0; j < 4; ++j) { const f32x4 s0 = *(const f32x4*)(sh + (j * 64 + lane) * 8), s1 = *(const f32x4*)(sh + (j * 64 + lane) * 8 + 4);
;                 s += (w[8 * j + 0] * s0.x + w[8 * j + 1] * s0.y) + (w[8 * j + 2] * s0.z + w[8 * j + 3] * s0.w) + (w[8 * j + 4] * s1.x + w[8 * j + 5] * s1.y) + (w[8 * j + 6] * s1.z + w[8 * j + 7] * s1.w); }
	v_lshlrev_b32_e32 v18, 16, v44
	v_and_b32_e32 v19, 0xffff0000, v44
	v_fmac_f32_e32 v12, v76, v18
	v_fmac_f32_e32 v12, v77, v19
	v_lshlrev_b32_e32 v20, 16, v60
	v_and_b32_e32 v21, 0xffff0000, v60
	v_fmac_f32_e32 v16, v76, v20
	v_fmac_f32_e32 v16, v77, v21
	v_lshlrev_b32_e32 v22, 16, v45
	v_and_b32_e32 v23, 0xffff0000, v45
	v_fmac_f32_e32 v12, v78, v22
	v_fmac_f32_e32 v12, v79, v23
	v_lshlrev_b32_e32 v24, 16, v61
	v_and_b32_e32 v25, 0xffff0000, v61
	v_fmac_f32_e32 v16, v78, v24
	v_fmac_f32_e32 v16, v79, v25
	v_lshlrev_b32_e32 v18, 16, v46
	v_and_b32_e32 v19, 0xffff0000, v46
	v_fmac_f32_e32 v12, v80, v18
	v_fmac_f32_e32 v12, v81, v19
	v_lshlrev_b32_e32 v20, 16, v62
	v_and_b32_e32 v21, 0xffff0000, v62
	v_fmac_f32_e32 v16, v80, v20
	v_fmac_f32_e32 v16, v81, v21
	v_lshlrev_b32_e32 v22, 16, v47
	v_and_b32_e32 v23, 0xffff0000, v47
	v_fmac_f32_e32 v12, v82, v22
	v_fmac_f32_e32 v12, v83, v23
	v_lshlrev_b32_e32 v24, 16, v63
	v_and_b32_e32 v25, 0xffff0000, v63
	v_fmac_f32_e32 v16, v82, v24
	v_fmac_f32_e32 v16, v83, v25
	v_lshlrev_b32_e32 v18, 16, v48
	v_and_b32_e32 v19, 0xffff0000, v48
	v_fmac_f32_e32 v12, v84, v18
	v_fmac_f32_e32 v12, v85, v19
	v_lshlrev_b32_e32 v20, 16, v64
	v_and_b32_e32 v21, 0xffff0000, v64
	v_fmac_f32_e32 v16, v84, v20
	v_fmac_f32_e32 v16, v85, v21
	v_lshlrev_b32_e32 v22, 16, v49
	v_and_b32_e32 v23, 0xffff0000, v49
	v_fmac_f32_e32 v12, v86, v22
	v_fmac_f32_e32 v12, v87, v23
	v_lshlrev_b32_e32 v24, 16, v65
	v_and_b32_e32 v25, 0xffff0000, v65
	v_fmac_f32_e32 v16, v86, v24
	v_fmac_f32_e32 v16, v87, v25
	v_lshlrev_b32_e32 v18, 16, v50
	v_and_b32_e32 v19, 0xffff0000, v50
	v_fmac_f32_e32 v12, v98, v18
	v_fmac_f32_e32 v12, v99, v19
	v_lshlrev_b32_e32 v20, 16, v66
	v_and_b32_e32 v21, 0xffff0000, v66
	v_fmac_f32_e32 v16, v98, v20
	v_fmac_f32_e32 v16, v99, v21
	v_lshlrev_b32_e32 v22, 16, v51
	v_and_b32_e32 v23, 0xffff0000, v51
	v_fmac_f32_e32 v12, v100, v22
	v_fmac_f32_e32 v12, v101, v23
	v_lshlrev_b32_e32 v24, 16, v67
	v_and_b32_e32 v25, 0xffff0000, v67
	v_fmac_f32_e32 v16, v100, v24
	v_fmac_f32_e32 v16, v101, v25
	v_lshlrev_b32_e32 v18, 16, v52
	v_and_b32_e32 v19, 0xffff0000, v52
	v_fmac_f32_e32 v12, v102, v18
	v_fmac_f32_e32 v12, v103, v19
	v_lshlrev_b32_e32 v20, 16, v68
	v_and_b32_e32 v21, 0xffff0000, v68
	v_fmac_f32_e32 v16, v102, v20
	v_fmac_f32_e32 v16, v103, v21
	v_lshlrev_b32_e32 v22, 16, v53
	v_and_b32_e32 v23, 0xffff0000, v53
	v_fmac_f32_e32 v12, v104, v22
	v_fmac_f32_e32 v12, v105, v23
	v_lshlrev_b32_e32 v24, 16, v69
	v_and_b32_e32 v25, 0xffff0000, v69
	v_fmac_f32_e32 v16, v104, v24
	v_fmac_f32_e32 v16, v105, v25
	v_lshlrev_b32_e32 v18, 16, v54
	v_and_b32_e32 v19, 0xffff0000, v54
	v_fmac_f32_e32 v12, v106, v18
	v_fmac_f32_e32 v12, v107, v19
	v_lshlrev_b32_e32 v20, 16, v70
	v_and_b32_e32 v21, 0xffff0000, v70
	v_fmac_f32_e32 v16, v106, v20
	v_fmac_f32_e32 v16, v107, v21
	v_lshlrev_b32_e32 v22, 16, v55
	v_and_b32_e32 v23, 0xffff0000, v55
	v_fmac_f32_e32 v12, v108, v22
	v_fmac_f32_e32 v12, v109, v23
	v_lshlrev_b32_e32 v24, 16, v71
	v_and_b32_e32 v25, 0xffff0000, v71
	v_fmac_f32_e32 v16, v108, v24
	v_fmac_f32_e32 v16, v109, v25
	v_lshlrev_b32_e32 v18, 16, v56
	v_and_b32_e32 v19, 0xffff0000, v56
	v_fmac_f32_e32 v12, v110, v18
	v_fmac_f32_e32 v12, v111, v19
	v_lshlrev_b32_e32 v20, 16, v72
	v_and_b32_e32 v21, 0xffff0000, v72
	v_fmac_f32_e32 v16, v110, v20
	v_fmac_f32_e32 v16, v111, v21
	v_lshlrev_b32_e32 v22, 16, v57
	v_and_b32_e32 v23, 0xffff0000, v57
	v_fmac_f32_e32 v12, v112, v22
	v_fmac_f32_e32 v12, v113, v23
	v_lshlrev_b32_e32 v24, 16, v73
	v_and_b32_e32 v25, 0xffff0000, v73
	v_fmac_f32_e32 v16, v112, v24
	v_fmac_f32_e32 v16, v113, v25
	v_lshlrev_b32_e32 v18, 16, v58
	v_and_b32_e32 v19, 0xffff0000, v58
	v_fmac_f32_e32 v12, v114, v18
	v_fmac_f32_e32 v12, v115, v19
	v_lshlrev_b32_e32 v20, 16, v74
	v_and_b32_e32 v21, 0xffff0000, v74
	v_fmac_f32_e32 v16, v114, v20
	v_fmac_f32_e32 v16, v115, v21
	v_lshlrev_b32_e32 v22, 16, v59
	v_and_b32_e32 v23, 0xffff0000, v59
	v_fmac_f32_e32 v12, v116, v22
	v_fmac_f32_e32 v12, v117, v23
	v_lshlrev_b32_e32 v24, 16, v75
	v_and_b32_e32 v25, 0xffff0000, v75
	v_fmac_f32_e32 v16, v116, v24
	v_fmac_f32_e32 v16, v117, v25
	s_add_u32 s100, s48, 0x2a000
	s_addc_u32 s101, s49, 0
	global_load_dwordx4 v[76:79], v0, s[100:101]
	global_load_dwordx4 v[80:83], v0, s[100:101] offset:16
	global_load_dwordx4 v[84:87], v0, s[100:101] offset:2048
	global_load_dwordx4 v[98:101], v0, s[100:101] offset:2064
	global_load_dwordx4 v[102:105], v1, s[100:101]
	global_load_dwordx4 v[106:109], v1, s[100:101] offset:16
	global_load_dwordx4 v[110:113], v1, s[100:101] offset:2048
	global_load_dwordx4 v[114:117], v1, s[100:101] offset:2064
	s_waitcnt vmcnt(0)
; __device__ __forceinline__ float wave_sum(float v) {
; #pragma unroll
;     for (int o = 1; o < 64; o <<= 1) v += __shfl_xor(v, o);
;     return v;
; }
; __device__ __forceinline__ void bias_phase(const bf16_t* W1T, const float* mod, float* cb, int gw, int NGW, int lane) {
;     ...
;             for (int j = 0; j < 4; ++j) { const f32x4 s0 = *(const f32x4*)(sh + (j * 64 + lane) * 8), s1 = *(const f32x4*)(sh + (j * 64 + lane) * 8 + 4);
;                 s += (w[8 * j + 0] * s0.x + w[8 * j + 1] * s0.y) + (w[8 * j + 2] * s0.z + w[8 * j + 3] * s0.w) + (w[8 * j + 4] * s1.x + w[8 * j + 5] * s1.y) + (w[8 * j + 6] * s1.z + w[8 * j + 7] * s1.w); }
;             s = wave_sum(s);
;             if (lane == 0) cb[(size_t)b * HID + n] = s; }
	v_lshlrev_b32_e32 v18, 16, v44
	v_and_b32_e32 v19, 0xffff0000, v44
	v_fmac_f32_e32 v13, v76, v18
	v_fmac_f32_e32 v13, v77, v19
	v_lshlrev_b32_e32 v20, 16, v60
	v_and_b32_e32 v21, 0xffff0000, v60
	v_fmac_f32_e32 v17, v76, v20
	v_fmac_f32_e32 v17, v77, v21
	v_lshlrev_b32_e32 v22, 16, v45
	v_and_b32_e32 v23, 0xffff0000, v45
	v_fmac_f32_e32 v13, v78, v22
	v_fmac_f32_e32 v13, v79, v23
	v_lshlrev_b32_e32 v24, 16, v61
	v_and_b32_e32 v25, 0xffff0000, v61
	v_fmac_f32_e32 v17, v78, v24
	v_fmac_f32_e32 v17, v79, v25
	v_lshlrev_b32_e32 v18, 16, v46
	v_and_b32_e32 v19, 0xffff0000, v46
	v_fmac_f32_e32 v13, v80, v18
	v_fmac_f32_e32 v13, v81, v19
	v_lshlrev_b32_e32 v20, 16, v62
	v_and_b32_e32 v21, 0xffff0000, v62
	v_fmac_f32_e32 v17, v80, v20
	v_fmac_f32_e32 v17, v81, v21
	v_lshlrev_b32_e32 v22, 16, v47
	v_and_b32_e32 v23, 0xffff0000, v47
	v_fmac_f32_e32 v13, v82, v22
	v_fmac_f32_e32 v13, v83, v23
	v_lshlrev_b32_e32 v24, 16, v63
	v_and_b32_e32 v25, 0xffff0000, v63
	v_fmac_f32_e32 v17, v82, v24
	v_fmac_f32_e32 v17, v83, v25
	v_lshlrev_b32_e32 v18, 16, v48
	v_and_b32_e32 v19, 0xffff0000, v48
	v_fmac_f32_e32 v13, v84, v18
	v_fmac_f32_e32 v13, v85, v19
	v_lshlrev_b32_e32 v20, 16, v64
	v_and_b32_e32 v21, 0xffff0000, v64
	v_fmac_f32_e32 v17, v84, v20
	v_fmac_f32_e32 v17, v85, v21
	v_lshlrev_b32_e32 v22, 16, v49
	v_and_b32_e32 v23, 0xffff0000, v49
	v_fmac_f32_e32 v13, v86, v22
	v_fmac_f32_e32 v13, v87, v23
	v_lshlrev_b32_e32 v24, 16, v65
	v_and_b32_e32 v25, 0xffff0000, v65
	v_fmac_f32_e32 v17, v86, v24
	v_fmac_f32_e32 v17, v87, v25
	v_lshlrev_b32_e32 v18, 16, v50
	v_and_b32_e32 v19, 0xffff0000, v50
	v_fmac_f32_e32 v13, v98, v18
	v_fmac_f32_e32 v13, v99, v19
	v_lshlrev_b32_e32 v20, 16, v66
	v_and_b32_e32 v21, 0xffff0000, v66
	v_fmac_f32_e32 v17, v98, v20
	v_fmac_f32_e32 v17, v99, v21
	v_lshlrev_b32_e32 v22, 16, v51
	v_and_b32_e32 v23, 0xffff0000, v51
	v_fmac_f32_e32 v13, v100, v22
	v_fmac_f32_e32 v13, v101, v23
	v_lshlrev_b32_e32 v24, 16, v67
	v_and_b32_e32 v25, 0xffff0000, v67
	v_fmac_f32_e32 v17, v100, v24
	v_fmac_f32_e32 v17, v101, v25
	v_lshlrev_b32_e32 v18, 16, v52
	v_and_b32_e32 v19, 0xffff0000, v52
	v_fmac_f32_e32 v13, v102, v18
	v_fmac_f32_e32 v13, v103, v19
	v_lshlrev_b32_e32 v20, 16, v68
	v_and_b32_e32 v21, 0xffff0000, v68
	v_fmac_f32_e32 v17, v102, v20
	v_fmac_f32_e32 v17, v103, v21
	v_lshlrev_b32_e32 v22, 16, v53
	v_and_b32_e32 v23, 0xffff0000, v53
	v_fmac_f32_e32 v13, v104, v22
	v_fmac_f32_e32 v13, v105, v23
	v_lshlrev_b32_e32 v24, 16, v69
	v_and_b32_e32 v25, 0xffff0000, v69
	v_fmac_f32_e32 v17, v104, v24
	v_fmac_f32_e32 v17, v105, v25
	v_lshlrev_b32_e32 v18, 16, v54
	v_and_b32_e32 v19, 0xffff0000, v54
	v_fmac_f32_e32 v13, v106, v18
	v_fmac_f32_e32 v13, v107, v19
	v_lshlrev_b32_e32 v20, 16, v70
	v_and_b32_e32 v21, 0xffff0000, v70
	v_fmac_f32_e32 v17, v106, v20
	v_fmac_f32_e32 v17, v107, v21
	v_lshlrev_b32_e32 v22, 16, v55
	v_and_b32_e32 v23, 0xffff0000, v55
	v_fmac_f32_e32 v13, v108, v22
	v_fmac_f32_e32 v13, v109, v23
	v_lshlrev_b32_e32 v24, 16, v71
	v_and_b32_e32 v25, 0xffff0000, v71
	v_fmac_f32_e32 v17, v108, v24
	v_fmac_f32_e32 v17, v109, v25
	v_lshlrev_b32_e32 v18, 16, v56
	v_and_b32_e32 v19, 0xffff0000, v56
	v_fmac_f32_e32 v13, v110, v18
	v_fmac_f32_e32 v13, v111, v19
	v_lshlrev_b32_e32 v20, 16, v72
	v_and_b32_e32 v21, 0xffff0000, v72
	v_fmac_f32_e32 v17, v110, v20
	v_fmac_f32_e32 v17, v111, v21
	v_lshlrev_b32_e32 v22, 16, v57
	v_and_b32_e32 v23, 0xffff0000, v57
	v_fmac_f32_e32 v13, v112, v22
	v_fmac_f32_e32 v13, v113, v23
	v_lshlrev_b32_e32 v24, 16, v73
	v_and_b32_e32 v25, 0xffff0000, v73
	v_fmac_f32_e32 v17, v112, v24
	v_fmac_f32_e32 v17, v113, v25
	v_lshlrev_b32_e32 v18, 16, v58
	v_and_b32_e32 v19, 0xffff0000, v58
	v_fmac_f32_e32 v13, v114, v18
	v_fmac_f32_e32 v13, v115, v19
	v_lshlrev_b32_e32 v20, 16, v74
	v_and_b32_e32 v21, 0xffff0000, v74
	v_fmac_f32_e32 v17, v114, v20
	v_fmac_f32_e32 v17, v115, v21
	v_lshlrev_b32_e32 v22, 16, v59
	v_and_b32_e32 v23, 0xffff0000, v59
	v_fmac_f32_e32 v13, v116, v22
	v_fmac_f32_e32 v13, v117, v23
	v_lshlrev_b32_e32 v24, 16, v75
	v_and_b32_e32 v25, 0xffff0000, v75
	v_fmac_f32_e32 v17, v116, v24
	v_fmac_f32_e32 v17, v117, v25
	ds_bpermute_b32 v44, v34, v2
	ds_bpermute_b32 v45, v34, v3
	ds_bpermute_b32 v46, v34, v4
	ds_bpermute_b32 v47, v34, v5
	ds_bpermute_b32 v48, v34, v6
	ds_bpermute_b32 v49, v34, v7
	ds_bpermute_b32 v50, v34, v8
	ds_bpermute_b32 v51, v34, v9
	s_waitcnt lgkmcnt(0)
	v_add_f32_e32 v2, v2, v44
	v_add_f32_e32 v3, v3, v45
	v_add_f32_e32 v4, v4, v46
	v_add_f32_e32 v5, v5, v47
	v_add_f32_e32 v6, v6, v48
	v_add_f32_e32 v7, v7, v49
	v_add_f32_e32 v8, v8, v50
	v_add_f32_e32 v9, v9, v51
	ds_bpermute_b32 v52, v34, v10
	ds_bpermute_b32 v53, v34, v11
	ds_bpermute_b32 v54, v34, v12
	ds_bpermute_b32 v55, v34, v13
	ds_bpermute_b32 v56, v34, v14
	ds_bpermute_b32 v57, v34, v15
	ds_bpermute_b32 v58, v34, v16
	ds_bpermute_b32 v59, v34, v17
	s_waitcnt lgkmcnt(0)
	v_add_f32_e32 v10, v10, v52
	v_add_f32_e32 v11, v11, v53
	v_add_f32_e32 v12, v12, v54
	v_add_f32_e32 v13, v13, v55
	v_add_f32_e32 v14, v14, v56
	v_add_f32_e32 v15, v15, v57
	v_add_f32_e32 v16, v16, v58
	v_add_f32_e32 v17, v17, v59
	ds_bpermute_b32 v44, v35, v2
	ds_bpermute_b32 v45, v35, v3
	ds_bpermute_b32 v46, v35, v4
	ds_bpermute_b32 v47, v35, v5
	ds_bpermute_b32 v48, v35, v6
	ds_bpermute_b32 v49, v35, v7
	ds_bpermute_b32 v50, v35, v8
	ds_bpermute_b32 v51, v35, v9
	s_waitcnt lgkmcnt(0)
; __device__ __forceinline__ float wave_sum(float v) {
; #pragma unroll
;     for (int o = 1; o < 64; o <<= 1) v += __shfl_xor(v, o);
;     return v;
; }
; __device__ __forceinline__ void bias_phase(const bf16_t* W1T, const float* mod, float* cb, int gw, int NGW, int lane) {
;     for (int n = gw; n < HID; n += NGW) {
;     ...
;             s = wave_sum(s);
;             if (lane == 0) cb[(size_t)b * HID + n] = s; }
	v_add_f32_e32 v2, v2, v44
	v_add_f32_e32 v3, v3, v45
	v_add_f32_e32 v4, v4, v46
	v_add_f32_e32 v5, v5, v47
	v_add_f32_e32 v6, v6, v48
	v_add_f32_e32 v7, v7, v49
	v_add_f32_e32 v8, v8, v50
	v_add_f32_e32 v9, v9, v51
	ds_bpermute_b32 v52, v35, v10
	ds_bpermute_b32 v53, v35, v11
	ds_bpermute_b32 v54, v35, v12
	ds_bpermute_b32 v55, v35, v13
	ds_bpermute_b32 v56, v35, v14
	ds_bpermute_b32 v57, v35, v15
	ds_bpermute_b32 v58, v35, v16
	ds_bpermute_b32 v59, v35, v17
	s_waitcnt lgkmcnt(0)
	v_add_f32_e32 v10, v10, v52
	v_add_f32_e32 v11, v11, v53
	v_add_f32_e32 v12, v12, v54
	v_add_f32_e32 v13, v13, v55
	v_add_f32_e32 v14, v14, v56
	v_add_f32_e32 v15, v15, v57
	v_add_f32_e32 v16, v16, v58
	v_add_f32_e32 v17, v17, v59
	ds_bpermute_b32 v44, v36, v2
	ds_bpermute_b32 v45, v36, v3
	ds_bpermute_b32 v46, v36, v4
	ds_bpermute_b32 v47, v36, v5
	ds_bpermute_b32 v48, v36, v6
	ds_bpermute_b32 v49, v36, v7
	ds_bpermute_b32 v50, v36, v8
	ds_bpermute_b32 v51, v36, v9
	s_waitcnt lgkmcnt(0)
	v_add_f32_e32 v2, v2, v44
	v_add_f32_e32 v3, v3, v45
	v_add_f32_e32 v4, v4, v46
	v_add_f32_e32 v5, v5, v47
	v_add_f32_e32 v6, v6, v48
	v_add_f32_e32 v7, v7, v49
	v_add_f32_e32 v8, v8, v50
	v_add_f32_e32 v9, v9, v51
	ds_bpermute_b32 v52, v36, v10
	ds_bpermute_b32 v53, v36, v11
	ds_bpermute_b32 v54, v36, v12
	ds_bpermute_b32 v55, v36, v13
	ds_bpermute_b32 v56, v36, v14
	ds_bpermute_b32 v57, v36, v15
	ds_bpermute_b32 v58, v36, v16
	ds_bpermute_b32 v59, v36, v17
	s_waitcnt lgkmcnt(0)
	v_add_f32_e32 v10, v10, v52
	v_add_f32_e32 v11, v11, v53
	v_add_f32_e32 v12, v12, v54
	v_add_f32_e32 v13, v13, v55
	v_add_f32_e32 v14, v14, v56
	v_add_f32_e32 v15, v15, v57
	v_add_f32_e32 v16, v16, v58
	v_add_f32_e32 v17, v17, v59
	ds_bpermute_b32 v44, v37, v2
	ds_bpermute_b32 v45, v37, v3
	ds_bpermute_b32 v46, v37, v4
	ds_bpermute_b32 v47, v37, v5
	ds_bpermute_b32 v48, v37, v6
	ds_bpermute_b32 v49, v37, v7
	ds_bpermute_b32 v50, v37, v8
	ds_bpermute_b32 v51, v37, v9
	s_waitcnt lgkmcnt(0)
	v_add_f32_e32 v2, v2, v44
	v_add_f32_e32 v3, v3, v45
	v_add_f32_e32 v4, v4, v46
	v_add_f32_e32 v5, v5, v47
	v_add_f32_e32 v6, v6, v48
	v_add_f32_e32 v7, v7, v49
	v_add_f32_e32 v8, v8, v50
	v_add_f32_e32 v9, v9, v51
	ds_bpermute_b32 v52, v37, v10
	ds_bpermute_b32 v53, v37, v11
	ds_bpermute_b32 v54, v37, v12
	ds_bpermute_b32 v55, v37, v13
	ds_bpermute_b32 v56, v37, v14
	ds_bpermute_b32 v57, v37, v15
	ds_bpermute_b32 v58, v37, v16
	ds_bpermute_b32 v59, v37, v17
	s_waitcnt lgkmcnt(0)
	v_add_f32_e32 v10, v10, v52
	v_add_f32_e32 v11, v11, v53
	v_add_f32_e32 v12, v12, v54
	v_add_f32_e32 v13, v13, v55
	v_add_f32_e32 v14, v14, v56
	v_add_f32_e32 v15, v15, v57
	v_add_f32_e32 v16, v16, v58
	v_add_f32_e32 v17, v17, v59
	ds_bpermute_b32 v44, v38, v2
	ds_bpermute_b32 v45, v38, v3
	ds_bpermute_b32 v46, v38, v4
	ds_bpermute_b32 v47, v38, v5
	ds_bpermute_b32 v48, v38, v6
	ds_bpermute_b32 v49, v38, v7
	ds_bpermute_b32 v50, v38, v8
	ds_bpermute_b32 v51, v38, v9
	s_waitcnt lgkmcnt(0)
	v_add_f32_e32 v2, v2, v44
	v_add_f32_e32 v3, v3, v45
	v_add_f32_e32 v4, v4, v46
	v_add_f32_e32 v5, v5, v47
	v_add_f32_e32 v6, v6, v48
	v_add_f32_e32 v7, v7, v49
	v_add_f32_e32 v8, v8, v50
	v_add_f32_e32 v9, v9, v51
	ds_bpermute_b32 v52, v38, v10
	ds_bpermute_b32 v53, v38, v11
	ds_bpermute_b32 v54, v38, v12
	ds_bpermute_b32 v55, v38, v13
	ds_bpermute_b32 v56, v38, v14
	ds_bpermute_b32 v57, v38, v15
	ds_bpermute_b32 v58, v38, v16
	ds_bpermute_b32 v59, v38, v17
	s_waitcnt lgkmcnt(0)
	v_add_f32_e32 v10, v10, v52
	v_add_f32_e32 v11, v11, v53
	v_add_f32_e32 v12, v12, v54
	v_add_f32_e32 v13, v13, v55
	v_add_f32_e32 v14, v14, v56
	v_add_f32_e32 v15, v15, v57
	v_add_f32_e32 v16, v16, v58
	v_add_f32_e32 v17, v17, v59
	ds_bpermute_b32 v44, v39, v2
	ds_bpermute_b32 v45, v39, v3
	ds_bpermute_b32 v46, v39, v4
	ds_bpermute_b32 v47, v39, v5
	ds_bpermute_b32 v48, v39, v6
	ds_bpermute_b32 v49, v39, v7
	ds_bpermute_b32 v50, v39, v8
	ds_bpermute_b32 v51, v39, v9
	s_waitcnt lgkmcnt(0)
	v_add_f32_e32 v2, v2, v44
	v_add_f32_e32 v3, v3, v45
	v_add_f32_e32 v4, v4, v46
	v_add_f32_e32 v5, v5, v47
	v_add_f32_e32 v6, v6, v48
	v_add_f32_e32 v7, v7, v49
	v_add_f32_e32 v8, v8, v50
	v_add_f32_e32 v9, v9, v51
	ds_bpermute_b32 v52, v39, v10
	ds_bpermute_b32 v53, v39, v11
	ds_bpermute_b32 v54, v39, v12
	ds_bpermute_b32 v55, v39, v13
	ds_bpermute_b32 v56, v39, v14
	ds_bpermute_b32 v57, v39, v15
	ds_bpermute_b32 v58, v39, v16
	ds_bpermute_b32 v59, v39, v17
	s_waitcnt lgkmcnt(0)
	v_add_f32_e32 v10, v10, v52
	v_add_f32_e32 v11, v11, v53
	v_add_f32_e32 v12, v12, v54
	v_add_f32_e32 v13, v13, v55
	v_add_f32_e32 v14, v14, v56
	v_add_f32_e32 v15, v15, v57
	v_add_f32_e32 v16, v16, v58
	v_add_f32_e32 v17, v17, v59
	s_and_saveexec_b64 s[10:11], s[4:5]
	global_store_dword v40, v2, s[8:9]
	global_store_dword v41, v3, s[8:9]
	global_store_dword v42, v4, s[8:9]
	global_store_dword v43, v5, s[8:9]
	s_add_u32 s8, s8, s2
	s_addc_u32 s9, s9, s3
	global_store_dword v40, v6, s[8:9]
	global_store_dword v41, v7, s[8:9]
	global_store_dword v42, v8, s[8:9]
	global_store_dword v43, v9, s[8:9]
	s_add_u32 s8, s8, s2
	s_addc_u32 s9, s9, s3
	global_store_dword v40, v10, s[8:9]
	global_store_dword v41, v11, s[8:9]
	global_store_dword v42, v12, s[8:9]
	global_store_dword v43, v13, s[8:9]
	s_add_u32 s8, s8, s2
	s_addc_u32 s9, s9, s3
	global_store_dword v40, v14, s[8:9]
	global_store_dword v41, v15, s[8:9]
	global_store_dword v42, v16, s[8:9]
	global_store_dword v43, v17, s[8:9]
	s_or_b64 exec, exec, s[10:11]
